# same as previous version but with the baseline's plain f32 ssq atomics (no partial-sum snapping)
# baseline (speedup 1.0000x reference)
; #define G3_LDA(buf, kt, i) __builtin_amdgcn_global_load_lds((const unsigned*)(ga + (size_t)((i) * 64) * lda + (kt) * 64), (lds_u32*)(sdst + (buf) * STAGE + (i) * 8192), 16, 0, 0)
; #define G3_LDB(buf, kt, i) __builtin_amdgcn_global_load_lds((const unsigned*)(gb + (size_t)((i) * 64) * ldb + (kt) * 64), (lds_u32*)(sdst + (buf) * STAGE + B_OFF + (i) * 8192), 16, 0, 0)
; DI void gemm3_mainloop(const int wave8, const int lane, const bf16_t* __restrict__ A, int lda, const bf16_t* __restrict__ Bt, int ldb, int K,
;                        unsigned char* smem, f32x4 (&acc)[8][4]) {
;     ...
;     asm volatile("s_waitcnt vmcnt(0)" ::: "memory");
;     G3_LDA(0, 0, 0); G3_LDA(0, 0, 1); G3_LDA(0, 0, 2); G3_LDA(0, 0, 3); G3_LDB(0, 0, 0); G3_LDB(0, 0, 1); G3_LDB(0, 0, 2); G3_LDB(0, 0, 3);
;     asm volatile("s_waitcnt vmcnt(0)" ::: "memory");
;     __builtin_amdgcn_s_barrier();
;     for (int kt = 0; kt < nk; kt += 2) { G3_STEP(0, 1, kt); G3_STEP(1, 0, kt + 1); }
.LBB0_90:
	ds_read_b128 v[128:131], v148 offset:32768
	ds_read_b128 v[168:171], v149
	ds_read_b128 v[156:159], v148 offset:34816
	ds_read_b128 v[160:163], v148 offset:36864
	ds_read_b128 v[164:167], v148 offset:38912
	ds_read_b128 v[172:175], v149 offset:2048
	ds_read_b128 v[176:179], v149 offset:4096
	ds_read_b128 v[180:183], v149 offset:6144
	ds_read_b128 v[184:187], v149 offset:8192
	ds_read_b128 v[188:191], v149 offset:10240
	ds_read_b128 v[192:195], v149 offset:12288
	ds_read_b128 v[196:199], v149 offset:14336
	s_waitcnt lgkmcnt(10)
	v_mfma_f32_16x16x32_bf16 v[112:115], v[128:131], v[168:171], v[112:115]
	s_mov_b64 s[8:9], 0x19dc5080
	s_mov_b32 m0, s88
	s_add_i32 s18, s6, 1
	s_waitcnt lgkmcnt(9)
	v_mfma_f32_16x16x32_bf16 v[124:127], v[156:159], v[168:171], v[124:127]
	s_add_i32 s7, s6, 2
	s_cmp_lt_u32 s6, 30
	s_waitcnt lgkmcnt(8)
	v_mfma_f32_16x16x32_bf16 v[120:123], v[160:163], v[168:171], v[120:123]
	s_waitcnt lgkmcnt(7)
	v_mfma_f32_16x16x32_bf16 v[116:119], v[164:167], v[168:171], v[116:119]
	v_lshl_add_u64 v[168:169], v[138:139], 0, v[132:133]
	v_lshl_add_u64 v[170:171], v[168:169], 0, s[8:9]
	s_mov_b64 s[8:9], 0x19e07080
	global_load_lds_dwordx4 v[170:171], off
	v_lshl_add_u64 v[170:171], v[168:169], 0, s[8:9]
	s_mov_b32 m0, s92
	s_mov_b64 s[8:9], 0x19e49080
	s_waitcnt lgkmcnt(6)
	v_mfma_f32_16x16x32_bf16 v[96:99], v[128:131], v[172:175], v[96:99]
	v_lshl_add_u64 v[138:139], v[138:139], 0, s[34:35]
	v_mfma_f32_16x16x32_bf16 v[108:111], v[156:159], v[172:175], v[108:111]
	v_mfma_f32_16x16x32_bf16 v[104:107], v[160:163], v[172:175], v[104:107]
	v_mfma_f32_16x16x32_bf16 v[100:103], v[164:167], v[172:175], v[100:103]
	global_load_lds_dwordx4 v[170:171], off
	v_lshl_add_u64 v[170:171], v[168:169], 0, s[8:9]
	s_mov_b32 m0, s93
	s_mov_b64 s[8:9], 0x19e8b080
	s_waitcnt lgkmcnt(5)
	v_mfma_f32_16x16x32_bf16 v[80:83], v[128:131], v[176:179], v[80:83]
	v_lshl_add_u64 v[168:169], v[168:169], 0, s[8:9]
	s_mov_b64 s[8:9], 0x245080
	v_mfma_f32_16x16x32_bf16 v[92:95], v[156:159], v[176:179], v[92:95]
	v_mfma_f32_16x16x32_bf16 v[88:91], v[160:163], v[176:179], v[88:91]
	v_mfma_f32_16x16x32_bf16 v[84:87], v[164:167], v[176:179], v[84:87]
	global_load_lds_dwordx4 v[170:171], off
	s_mov_b32 m0, s94
	s_waitcnt lgkmcnt(4)
	v_mfma_f32_16x16x32_bf16 v[64:67], v[128:131], v[180:183], v[64:67]
	v_mfma_f32_16x16x32_bf16 v[76:79], v[156:159], v[180:183], v[76:79]
	v_mfma_f32_16x16x32_bf16 v[72:75], v[160:163], v[180:183], v[72:75]
	v_mfma_f32_16x16x32_bf16 v[68:71], v[164:167], v[180:183], v[68:71]
	global_load_lds_dwordx4 v[168:169], off
	s_mov_b32 m0, s89
	s_waitcnt lgkmcnt(3)
	v_mfma_f32_16x16x32_bf16 v[48:51], v[128:131], v[184:187], v[48:51]
	v_mfma_f32_16x16x32_bf16 v[60:63], v[156:159], v[184:187], v[60:63]
	v_mfma_f32_16x16x32_bf16 v[56:59], v[160:163], v[184:187], v[56:59]
	v_mfma_f32_16x16x32_bf16 v[52:55], v[164:167], v[184:187], v[52:55]
	s_waitcnt lgkmcnt(2)
	v_mfma_f32_16x16x32_bf16 v[32:35], v[128:131], v[188:191], v[32:35]
	v_mfma_f32_16x16x32_bf16 v[44:47], v[156:159], v[188:191], v[44:47]
	v_mfma_f32_16x16x32_bf16 v[40:43], v[160:163], v[188:191], v[40:43]
	v_mfma_f32_16x16x32_bf16 v[36:39], v[164:167], v[188:191], v[36:39]
	s_waitcnt lgkmcnt(1)
	v_mfma_f32_16x16x32_bf16 v[12:15], v[128:131], v[192:195], v[12:15]
	v_mfma_f32_16x16x32_bf16 v[24:27], v[156:159], v[192:195], v[24:27]
	v_mfma_f32_16x16x32_bf16 v[20:23], v[160:163], v[192:195], v[20:23]
	v_mfma_f32_16x16x32_bf16 v[16:19], v[164:167], v[192:195], v[16:19]
	s_waitcnt lgkmcnt(0)
	v_mfma_f32_16x16x32_bf16 v[0:3], v[128:131], v[196:199], v[0:3]
	v_mfma_f32_16x16x32_bf16 v[8:11], v[156:159], v[196:199], v[8:11]
	v_mfma_f32_16x16x32_bf16 v[4:7], v[160:163], v[196:199], v[4:7]
	v_mfma_f32_16x16x32_bf16 v[28:31], v[164:167], v[196:199], v[28:31]
	ds_read_b128 v[128:131], v150 offset:32768
	ds_read_b128 v[168:171], v151
	ds_read_b128 v[156:159], v150 offset:34816
	ds_read_b128 v[160:163], v150 offset:36864
	ds_read_b128 v[164:167], v150 offset:38912
	ds_read_b128 v[172:175], v151 offset:2048
	ds_read_b128 v[176:179], v151 offset:4096
	ds_read_b128 v[180:183], v151 offset:6144
	ds_read_b128 v[184:187], v151 offset:8192
	ds_read_b128 v[188:191], v151 offset:10240
	ds_read_b128 v[192:195], v151 offset:12288
	ds_read_b128 v[196:199], v151 offset:14336
	s_waitcnt lgkmcnt(10)
	v_mfma_f32_16x16x32_bf16 v[112:115], v[128:131], v[168:171], v[112:115]
	s_waitcnt lgkmcnt(9)
	v_mfma_f32_16x16x32_bf16 v[124:127], v[156:159], v[168:171], v[124:127]
	s_waitcnt lgkmcnt(8)
	v_mfma_f32_16x16x32_bf16 v[120:123], v[160:163], v[168:171], v[120:123]
	s_waitcnt lgkmcnt(7)
	v_mfma_f32_16x16x32_bf16 v[116:119], v[164:167], v[168:171], v[116:119]
	v_lshl_add_u64 v[168:169], v[140:141], 0, v[132:133]
	v_lshl_add_u64 v[170:171], v[168:169], 0, s[8:9]
	s_mov_b64 s[8:9], 0x287080
	global_load_lds_dwordx4 v[170:171], off
	v_lshl_add_u64 v[170:171], v[168:169], 0, s[8:9]
	s_mov_b32 m0, s95
	s_waitcnt lgkmcnt(6)
	v_mfma_f32_16x16x32_bf16 v[96:99], v[128:131], v[172:175], v[96:99]
	s_cselect_b64 s[8:9], -1, 0
	s_and_b64 vcc, s[8:9], exec
	s_cselect_b32 s6, s7, s18
	v_mfma_f32_16x16x32_bf16 v[108:111], v[156:159], v[172:175], v[108:111]
	s_lshl_b32 s18, s6, 7
	v_lshl_add_u64 v[140:141], v[140:141], 0, s[34:35]
	s_mov_b32 s6, s7
	v_mfma_f32_16x16x32_bf16 v[104:107], v[160:163], v[172:175], v[104:107]
	v_mfma_f32_16x16x32_bf16 v[100:103], v[164:167], v[172:175], v[100:103]
	global_load_lds_dwordx4 v[170:171], off
	v_lshl_add_u64 v[170:171], v[168:169], 0, s[28:29]
	s_mov_b32 m0, s96
	s_waitcnt lgkmcnt(5)
; #define G3_LDA(buf, kt, i) __builtin_amdgcn_global_load_lds((const unsigned*)(ga + (size_t)((i) * 64) * lda + (kt) * 64), (lds_u32*)(sdst + (buf) * STAGE + (i) * 8192), 16, 0, 0)
; #define G3_LDB(buf, kt, i) __builtin_amdgcn_global_load_lds((const unsigned*)(gb + (size_t)((i) * 64) * ldb + (kt) * 64), (lds_u32*)(sdst + (buf) * STAGE + B_OFF + (i) * 8192), 16, 0, 0)
; DI void gemm3_mainloop(const int wave8, const int lane, const bf16_t* __restrict__ A, int lda, const bf16_t* __restrict__ Bt, int ldb, int K,
;                        unsigned char* smem, f32x4 (&acc)[8][4]) {
;     ...
;     asm volatile("s_waitcnt vmcnt(0)" ::: "memory");
;     G3_LDA(0, 0, 0); G3_LDA(0, 0, 1); G3_LDA(0, 0, 2); G3_LDA(0, 0, 3); G3_LDB(0, 0, 0); G3_LDB(0, 0, 1); G3_LDB(0, 0, 2); G3_LDB(0, 0, 3);
;     asm volatile("s_waitcnt vmcnt(0)" ::: "memory");
;     __builtin_amdgcn_s_barrier();
;     for (int kt = 0; kt < nk; kt += 2) { G3_STEP(0, 1, kt); G3_STEP(1, 0, kt + 1); }
	v_mfma_f32_16x16x32_bf16 v[80:83], v[128:131], v[176:179], v[80:83]
	v_lshl_add_u64 v[168:169], v[168:169], 0, s[30:31]
	v_mfma_f32_16x16x32_bf16 v[92:95], v[156:159], v[176:179], v[92:95]
	v_mfma_f32_16x16x32_bf16 v[88:91], v[160:163], v[176:179], v[88:91]
	v_mfma_f32_16x16x32_bf16 v[84:87], v[164:167], v[176:179], v[84:87]
	global_load_lds_dwordx4 v[170:171], off
	s_mov_b32 m0, s97
	s_waitcnt lgkmcnt(4)
	v_mfma_f32_16x16x32_bf16 v[64:67], v[128:131], v[180:183], v[64:67]
	v_mfma_f32_16x16x32_bf16 v[76:79], v[156:159], v[180:183], v[76:79]
	v_mfma_f32_16x16x32_bf16 v[72:75], v[160:163], v[180:183], v[72:75]
	v_mfma_f32_16x16x32_bf16 v[68:71], v[164:167], v[180:183], v[68:71]
	global_load_lds_dwordx4 v[168:169], off
	s_waitcnt lgkmcnt(3)
	v_mfma_f32_16x16x32_bf16 v[48:51], v[128:131], v[184:187], v[48:51]
	s_mov_b32 m0, s0
	v_mfma_f32_16x16x32_bf16 v[60:63], v[156:159], v[184:187], v[60:63]
	v_mfma_f32_16x16x32_bf16 v[56:59], v[160:163], v[184:187], v[56:59]
	v_mfma_f32_16x16x32_bf16 v[52:55], v[164:167], v[184:187], v[52:55]
	s_waitcnt lgkmcnt(2)
	v_mfma_f32_16x16x32_bf16 v[32:35], v[128:131], v[188:191], v[32:35]
	v_mfma_f32_16x16x32_bf16 v[44:47], v[156:159], v[188:191], v[44:47]
	v_mfma_f32_16x16x32_bf16 v[40:43], v[160:163], v[188:191], v[40:43]
	v_mfma_f32_16x16x32_bf16 v[36:39], v[164:167], v[188:191], v[36:39]
	s_waitcnt lgkmcnt(1)
	v_mfma_f32_16x16x32_bf16 v[12:15], v[128:131], v[192:195], v[12:15]
	v_mfma_f32_16x16x32_bf16 v[24:27], v[156:159], v[192:195], v[24:27]
	v_mfma_f32_16x16x32_bf16 v[20:23], v[160:163], v[192:195], v[20:23]
	v_mfma_f32_16x16x32_bf16 v[16:19], v[164:167], v[192:195], v[16:19]
	s_waitcnt lgkmcnt(0)
	v_mfma_f32_16x16x32_bf16 v[0:3], v[128:131], v[196:199], v[0:3]
	s_waitcnt vmcnt(0)
	s_barrier
	v_mfma_f32_16x16x32_bf16 v[8:11], v[156:159], v[196:199], v[8:11]
	v_mfma_f32_16x16x32_bf16 v[4:7], v[160:163], v[196:199], v[4:7]
	v_mfma_f32_16x16x32_bf16 v[28:31], v[164:167], v[196:199], v[28:31]
	ds_read_b128 v[128:131], v152
	ds_read_b128 v[168:171], v153
	ds_read_b128 v[156:159], v152 offset:2048
	ds_read_b128 v[160:163], v152 offset:4096
	ds_read_b128 v[164:167], v152 offset:6144
	ds_read_b128 v[172:175], v153 offset:2048
	ds_read_b128 v[176:179], v153 offset:4096
	ds_read_b128 v[180:183], v153 offset:6144
	ds_read_b128 v[184:187], v153 offset:8192
	ds_read_b128 v[188:191], v153 offset:10240
	ds_read_b128 v[192:195], v153 offset:12288
	ds_read_b128 v[196:199], v153 offset:14336
	s_waitcnt lgkmcnt(10)
	v_mfma_f32_16x16x32_bf16 v[112:115], v[128:131], v[168:171], v[112:115]
	s_waitcnt lgkmcnt(9)
	v_mfma_f32_16x16x32_bf16 v[124:127], v[156:159], v[168:171], v[124:127]
	s_waitcnt lgkmcnt(8)
	v_mfma_f32_16x16x32_bf16 v[120:123], v[160:163], v[168:171], v[120:123]
	s_waitcnt lgkmcnt(7)
	v_mfma_f32_16x16x32_bf16 v[116:119], v[164:167], v[168:171], v[116:119]
	v_lshl_add_u64 v[168:169], v[134:135], 0, s[18:19]
	global_load_lds_dwordx4 v[168:169], off
	v_lshl_add_u64 v[170:171], v[168:169], 0, s[22:23]
	s_mov_b32 m0, s55
	s_waitcnt lgkmcnt(6)
	v_mfma_f32_16x16x32_bf16 v[96:99], v[128:131], v[172:175], v[96:99]
	v_mfma_f32_16x16x32_bf16 v[108:111], v[156:159], v[172:175], v[108:111]
	v_mfma_f32_16x16x32_bf16 v[104:107], v[160:163], v[172:175], v[104:107]
	v_mfma_f32_16x16x32_bf16 v[100:103], v[164:167], v[172:175], v[100:103]
	global_load_lds_dwordx4 v[170:171], off
	v_lshl_add_u64 v[170:171], v[168:169], 0, s[24:25]
	s_mov_b32 m0, s87
	s_waitcnt lgkmcnt(5)
	v_mfma_f32_16x16x32_bf16 v[80:83], v[128:131], v[176:179], v[80:83]
	v_lshl_add_u64 v[168:169], v[168:169], 0, s[26:27]
	v_mfma_f32_16x16x32_bf16 v[92:95], v[156:159], v[176:179], v[92:95]
	v_mfma_f32_16x16x32_bf16 v[88:91], v[160:163], v[176:179], v[88:91]
	v_mfma_f32_16x16x32_bf16 v[84:87], v[164:167], v[176:179], v[84:87]
	global_load_lds_dwordx4 v[170:171], off
	s_mov_b32 m0, s69
	s_waitcnt lgkmcnt(4)
	v_mfma_f32_16x16x32_bf16 v[64:67], v[128:131], v[180:183], v[64:67]
	v_mfma_f32_16x16x32_bf16 v[76:79], v[156:159], v[180:183], v[76:79]
	v_mfma_f32_16x16x32_bf16 v[72:75], v[160:163], v[180:183], v[72:75]
	v_mfma_f32_16x16x32_bf16 v[68:71], v[164:167], v[180:183], v[68:71]
	global_load_lds_dwordx4 v[168:169], off
	s_mov_b32 m0, s68
	s_waitcnt lgkmcnt(3)
	v_mfma_f32_16x16x32_bf16 v[48:51], v[128:131], v[184:187], v[48:51]
	v_mfma_f32_16x16x32_bf16 v[60:63], v[156:159], v[184:187], v[60:63]
	v_mfma_f32_16x16x32_bf16 v[56:59], v[160:163], v[184:187], v[56:59]
	v_mfma_f32_16x16x32_bf16 v[52:55], v[164:167], v[184:187], v[52:55]
	s_waitcnt lgkmcnt(2)
	v_mfma_f32_16x16x32_bf16 v[32:35], v[128:131], v[188:191], v[32:35]
	v_mfma_f32_16x16x32_bf16 v[44:47], v[156:159], v[188:191], v[44:47]
	v_mfma_f32_16x16x32_bf16 v[40:43], v[160:163], v[188:191], v[40:43]
	v_mfma_f32_16x16x32_bf16 v[36:39], v[164:167], v[188:191], v[36:39]
	s_waitcnt lgkmcnt(1)
	v_mfma_f32_16x16x32_bf16 v[12:15], v[128:131], v[192:195], v[12:15]
	v_mfma_f32_16x16x32_bf16 v[24:27], v[156:159], v[192:195], v[24:27]
	v_mfma_f32_16x16x32_bf16 v[20:23], v[160:163], v[192:195], v[20:23]
	v_mfma_f32_16x16x32_bf16 v[16:19], v[164:167], v[192:195], v[16:19]
	s_waitcnt lgkmcnt(0)
	v_mfma_f32_16x16x32_bf16 v[0:3], v[128:131], v[196:199], v[0:3]
	v_mfma_f32_16x16x32_bf16 v[8:11], v[156:159], v[196:199], v[8:11]
	v_mfma_f32_16x16x32_bf16 v[4:7], v[160:163], v[196:199], v[4:7]
	v_mfma_f32_16x16x32_bf16 v[28:31], v[164:167], v[196:199], v[28:31]
	ds_read_b128 v[156:159], v154
	ds_read_b128 v[168:171], v155
	ds_read_b128 v[160:163], v154 offset:2048
	ds_read_b128 v[164:167], v154 offset:4096
	ds_read_b128 v[128:131], v154 offset:6144
	ds_read_b128 v[172:175], v155 offset:2048
	ds_read_b128 v[176:179], v155 offset:4096
	ds_read_b128 v[180:183], v155 offset:6144
	ds_read_b128 v[184:187], v155 offset:8192
	ds_read_b128 v[188:191], v155 offset:10240
	ds_read_b128 v[192:195], v155 offset:12288
	ds_read_b128 v[196:199], v155 offset:14336
	s_waitcnt lgkmcnt(10)
; DI unsigned pk2(float a, float b) { f2_t v = {a, b}; bf2_t r = __builtin_convertvector(v, bf2_t); return __builtin_bit_cast(unsigned, r); }
; #define G3_LDA(buf, kt, i) __builtin_amdgcn_global_load_lds((const unsigned*)(ga + (size_t)((i) * 64) * lda + (kt) * 64), (lds_u32*)(sdst + (buf) * STAGE + (i) * 8192), 16, 0, 0)
; #define G3_LDB(buf, kt, i) __builtin_amdgcn_global_load_lds((const unsigned*)(gb + (size_t)((i) * 64) * ldb + (kt) * 64), (lds_u32*)(sdst + (buf) * STAGE + B_OFF + (i) * 8192), 16, 0, 0)
; DI void gemm3_mainloop(const int wave8, const int lane, const bf16_t* __restrict__ A, int lda, const bf16_t* __restrict__ Bt, int ldb, int K,
;                        unsigned char* smem, f32x4 (&acc)[8][4]) {
;     ...
;     asm volatile("s_waitcnt vmcnt(0)" ::: "memory");
;     G3_LDA(0, 0, 0); G3_LDA(0, 0, 1); G3_LDA(0, 0, 2); G3_LDA(0, 0, 3); G3_LDB(0, 0, 0); G3_LDB(0, 0, 1); G3_LDB(0, 0, 2); G3_LDB(0, 0, 3);
;     asm volatile("s_waitcnt vmcnt(0)" ::: "memory");
;     __builtin_amdgcn_s_barrier();
;     for (int kt = 0; kt < nk; kt += 2) { G3_STEP(0, 1, kt); G3_STEP(1, 0, kt + 1); }
; DI void phase1(const Params& p, unsigned char* smem) {
;     ...
;         const int c128 = nt * 2 + (wn >> 1);
;         if (c128 >= 47) return;
;         bf16_t* dst; int ld, c0;
;         if (c128 < 23) { dst = pa; ld = LDPA; c0 = c128 * 128; } else { dst = pb; ld = LDPB; c0 = (c128 - 23) * 128; }
; #pragma unroll
;         for (int i = 0; i < 8; ++i) {
;             const int m = mt * 256 + wm * 128 + i * 16 + fr;
;             float ss = 0.f;
; #pragma unroll
;             for (int j = 0; j < 4; ++j) {
;                 const f32x4 v = acc[i][j];
;                 ss += v.x * v.x + v.y * v.y + v.z * v.z + v.w * v.w;
;                 u32x2 o; o.x = pk2(v.x, v.y); o.y = pk2(v.z, v.w);
;                 *(u32x2*)(dst + (size_t)m * ld + c0 + (wn & 1) * 64 + j * 16 + fq * 4) = o;
;             }
;             if (c128 < 6) {
;                 ss += __shfl_xor(ss, 16); ss += __shfl_xor(ss, 32);
;                 if (fq == 0) atomicAdd(ssq + (c128 < 4 ? 0 : T_) + m, ss);
	v_mfma_f32_16x16x32_bf16 v[112:115], v[156:159], v[168:171], v[112:115]
	s_waitcnt lgkmcnt(9)
	v_mfma_f32_16x16x32_bf16 v[124:127], v[160:163], v[168:171], v[124:127]
	s_waitcnt lgkmcnt(8)
	v_mfma_f32_16x16x32_bf16 v[120:123], v[164:167], v[168:171], v[120:123]
	s_waitcnt lgkmcnt(7)
	v_mfma_f32_16x16x32_bf16 v[116:119], v[128:131], v[168:171], v[116:119]
	v_lshl_add_u64 v[168:169], v[136:137], 0, s[18:19]
	global_load_lds_dwordx4 v[168:169], off
	v_lshl_add_u64 v[170:171], v[168:169], 0, s[22:23]
	s_mov_b32 m0, s39
	s_waitcnt lgkmcnt(6)
	v_mfma_f32_16x16x32_bf16 v[96:99], v[156:159], v[172:175], v[96:99]
	v_mfma_f32_16x16x32_bf16 v[108:111], v[160:163], v[172:175], v[108:111]
	v_mfma_f32_16x16x32_bf16 v[104:107], v[164:167], v[172:175], v[104:107]
	v_mfma_f32_16x16x32_bf16 v[100:103], v[128:131], v[172:175], v[100:103]
	global_load_lds_dwordx4 v[170:171], off
	v_lshl_add_u64 v[170:171], v[168:169], 0, s[24:25]
	s_mov_b32 m0, s38
	s_waitcnt lgkmcnt(5)
	v_mfma_f32_16x16x32_bf16 v[80:83], v[156:159], v[176:179], v[80:83]
	v_lshl_add_u64 v[168:169], v[168:169], 0, s[26:27]
	v_mfma_f32_16x16x32_bf16 v[92:95], v[160:163], v[176:179], v[92:95]
	v_mfma_f32_16x16x32_bf16 v[88:91], v[164:167], v[176:179], v[88:91]
	v_mfma_f32_16x16x32_bf16 v[84:87], v[128:131], v[176:179], v[84:87]
	global_load_lds_dwordx4 v[170:171], off
	s_mov_b32 m0, s1
	s_waitcnt lgkmcnt(4)
	v_mfma_f32_16x16x32_bf16 v[64:67], v[156:159], v[180:183], v[64:67]
	v_mfma_f32_16x16x32_bf16 v[76:79], v[160:163], v[180:183], v[76:79]
	v_mfma_f32_16x16x32_bf16 v[72:75], v[164:167], v[180:183], v[72:75]
	v_mfma_f32_16x16x32_bf16 v[68:71], v[128:131], v[180:183], v[68:71]
	global_load_lds_dwordx4 v[168:169], off
	s_waitcnt lgkmcnt(3)
	v_mfma_f32_16x16x32_bf16 v[48:51], v[156:159], v[184:187], v[48:51]
	v_mfma_f32_16x16x32_bf16 v[60:63], v[160:163], v[184:187], v[60:63]
	v_mfma_f32_16x16x32_bf16 v[56:59], v[164:167], v[184:187], v[56:59]
	v_mfma_f32_16x16x32_bf16 v[52:55], v[128:131], v[184:187], v[52:55]
	s_waitcnt lgkmcnt(2)
	v_mfma_f32_16x16x32_bf16 v[32:35], v[156:159], v[188:191], v[32:35]
	v_mfma_f32_16x16x32_bf16 v[44:47], v[160:163], v[188:191], v[44:47]
	v_mfma_f32_16x16x32_bf16 v[40:43], v[164:167], v[188:191], v[40:43]
	v_mfma_f32_16x16x32_bf16 v[36:39], v[128:131], v[188:191], v[36:39]
	s_waitcnt lgkmcnt(1)
	v_mfma_f32_16x16x32_bf16 v[12:15], v[156:159], v[192:195], v[12:15]
	v_mfma_f32_16x16x32_bf16 v[24:27], v[160:163], v[192:195], v[24:27]
	v_mfma_f32_16x16x32_bf16 v[20:23], v[164:167], v[192:195], v[20:23]
	v_mfma_f32_16x16x32_bf16 v[16:19], v[128:131], v[192:195], v[16:19]
	s_waitcnt lgkmcnt(0)
	v_mfma_f32_16x16x32_bf16 v[0:3], v[156:159], v[196:199], v[0:3]
	s_waitcnt vmcnt(0)
	s_barrier
	v_mfma_f32_16x16x32_bf16 v[8:11], v[160:163], v[196:199], v[8:11]
	v_mfma_f32_16x16x32_bf16 v[4:7], v[164:167], v[196:199], v[4:7]
	v_mfma_f32_16x16x32_bf16 v[28:31], v[128:131], v[196:199], v[28:31]
	s_cbranch_vccnz .LBB0_90
	s_lshl_b32 s5, s5, 1
	s_or_b32 s36, s5, s44
	s_cmp_gt_i32 s36, 46
	s_cbranch_scc1 .LBB0_88
	s_lshl_b32 s5, s36, 7
	s_add_i32 s6, s5, 0xfffff480
	s_cmp_lt_i32 s36, 23
	s_cselect_b32 s6, s5, s6
	s_cselect_b32 s5, s48, 0xddc5000
	s_cselect_b32 s75, s46, 0xc00
	s_add_u32 s8, s72, s5
	s_addc_u32 s9, s73, 0
	s_lshl_b32 s4, s4, 8
	s_add_i32 s4, s4, s54
	s_ashr_i32 s7, s6, 31
	v_and_or_b32 v130, v147, 15, s4
	s_lshl_b64 s[4:5], s[6:7], 1
	s_add_u32 s4, s8, s4
	s_addc_u32 s5, s9, s5
	s_add_u32 s4, s4, s49
	s_addc_u32 s5, s5, 0
	v_lshlrev_b32_e32 v132, 3, v145
	v_lshl_add_u64 v[128:129], s[4:5], 0, v[132:133]
	v_mov_b32_e32 v132, v130
	v_mad_u64_u32 v[130:131], s[4:5], s75, v130, 0
	v_lshl_add_u64 v[130:131], v[130:131], 1, v[128:129]
	v_cvt_pk_bf16_f32 v134, v112, v113
	v_cvt_pk_bf16_f32 v135, v114, v115
	s_cmp_lt_i32 s36, 6
	global_store_dwordx2 v[130:131], v[134:135], off
	v_cvt_pk_bf16_f32 v134, v124, v125
	v_cvt_pk_bf16_f32 v135, v126, v127
	s_cselect_b64 s[6:7], -1, 0
	s_cmp_lt_i32 s36, 4
	global_store_dwordx2 v[130:131], v[134:135], off offset:32
	v_cvt_pk_bf16_f32 v134, v120, v121
	v_cvt_pk_bf16_f32 v135, v122, v123
	s_cselect_b32 s18, 0, 0x8000
	s_cmp_gt_i32 s36, 5
	v_cmp_gt_u32_e64 s[8:9], 16, v146
	global_store_dwordx2 v[130:131], v[134:135], off offset:64
	v_cvt_pk_bf16_f32 v134, v116, v117
	v_cvt_pk_bf16_f32 v135, v118, v119
	global_store_dwordx2 v[130:131], v[134:135], off offset:96
	s_cbranch_scc1 .LBB0_96
	v_mul_f32_e32 v130, v113, v113
	v_mul_f32_e32 v125, v125, v125
	v_fmac_f32_e32 v130, v112, v112
	v_fmac_f32_e32 v125, v124, v124
	v_mul_f32_e32 v121, v121, v121
	v_fmac_f32_e32 v130, v114, v114
	v_fmac_f32_e32 v125, v126, v126
	v_fmac_f32_e32 v121, v120, v120
	v_mul_f32_e32 v117, v117, v117
	v_fmac_f32_e32 v130, v115, v115
	v_fmac_f32_e32 v125, v127, v127
	v_fmac_f32_e32 v121, v122, v122
	v_fmac_f32_e32 v117, v116, v116
	v_add_f32_e32 v124, v130, v125
	v_fmac_f32_e32 v121, v123, v123
	v_fmac_f32_e32 v117, v118, v118
	v_add_f32_e32 v120, v124, v121
	v_fmac_f32_e32 v117, v119, v119
	v_add_f32_e32 v116, v120, v117
	ds_bpermute_b32 v117, v144, v116
	s_waitcnt lgkmcnt(0)
	v_add_f32_e32 v116, v116, v117
	ds_bpermute_b32 v117, v241, v116
	s_and_saveexec_b64 s[4:5], s[8:9]
	s_cbranch_execz .LBB0_95
	s_lshl_b32 s37, s18, 2
	s_add_u32 s76, s12, s37
	s_addc_u32 s77, s13, 0
	s_waitcnt lgkmcnt(0)
	v_add_f32_e32 v118, v116, v117
	v_lshl_add_u64 v[116:117], v[132:133], 2, s[76:77]
	global_atomic_add_f32 v[116:117], v118, off
